# v27 plus per-phase vmcnt(10) DMA-landing waits in the GEMM K-loops instead of two vmcnt(6) per iteration (every stage gets at least 5 phases to land)
# baseline (speedup 1.0000x reference)
.LBB0_204:
	s_add_u32 s44, s40, 0xfff80080
	s_addc_u32 s45, s41, -1
	s_and_b64 s[4:5], s[42:43], exec
	s_cselect_b32 s45, s31, s45
	s_cselect_b32 s44, s65, s44
	s_add_i32 s70, 0, 0x10000
	v_add_u32_e32 v168, s70, v145
	ds_read_b128 v[156:159], v168
	ds_read_b128 v[160:163], v168 offset:1024
	ds_read_b128 v[164:167], v168 offset:2048
	ds_read_b128 v[168:171], v168 offset:3072
	s_and_b64 s[4:5], s[42:43], exec
	s_cselect_b32 s5, s29, s68
	s_cselect_b32 s4, s66, s67
	v_lshl_add_u64 v[176:177], s[40:41], 0, v[136:137]
	s_add_i32 m0, s39, 0xc000
	ds_read_b128 v[172:175], v147
	ds_read_b128 v[180:183], v147 offset:1024
	ds_read_b128 v[184:187], v147 offset:2048
	ds_read_b128 v[188:191], v147 offset:3072
	ds_read_b128 v[192:195], v147 offset:4096
	ds_read_b128 v[216:219], v147 offset:5120
	ds_read_b128 v[220:223], v147 offset:6144
	ds_read_b128 v[224:227], v147 offset:7168
	global_load_lds_dwordx4 v[176:177], off
	v_lshl_add_u64 v[176:177], s[40:41], 0, v[138:139]
	s_add_i32 m0, s39, 0xe000
	s_nop 0
	global_load_lds_dwordx4 v[176:177], off
	s_waitcnt lgkmcnt(8)
	s_waitcnt vmcnt(10)
	s_barrier
	s_waitcnt lgkmcnt(0)
	s_waitcnt lgkmcnt(0)
	v_mfma_f32_16x16x32_bf16 v[126:129], v[156:159], v[172:175], v[126:129]
	v_mfma_f32_16x16x32_bf16 v[122:125], v[164:167], v[172:175], v[122:125]
	v_mfma_f32_16x16x32_bf16 v[110:113], v[156:159], v[184:187], v[110:113]
	v_mfma_f32_16x16x32_bf16 v[106:109], v[164:167], v[184:187], v[106:109]
	v_mfma_f32_16x16x32_bf16 v[94:97], v[156:159], v[192:195], v[94:97]
	v_mfma_f32_16x16x32_bf16 v[90:93], v[164:167], v[192:195], v[90:93]
	v_mfma_f32_16x16x32_bf16 v[78:81], v[156:159], v[220:223], v[78:81]
	v_mfma_f32_16x16x32_bf16 v[74:77], v[164:167], v[220:223], v[74:77]
	v_mfma_f32_16x16x32_bf16 v[126:129], v[160:163], v[180:183], v[126:129]
	v_mfma_f32_16x16x32_bf16 v[122:125], v[168:171], v[180:183], v[122:125]
	v_mfma_f32_16x16x32_bf16 v[110:113], v[160:163], v[188:191], v[110:113]
	v_mfma_f32_16x16x32_bf16 v[106:109], v[168:171], v[188:191], v[106:109]
	v_mfma_f32_16x16x32_bf16 v[94:97], v[160:163], v[216:219], v[94:97]
	v_mfma_f32_16x16x32_bf16 v[90:93], v[168:171], v[216:219], v[90:93]
	v_mfma_f32_16x16x32_bf16 v[78:81], v[160:163], v[224:227], v[78:81]
	v_mfma_f32_16x16x32_bf16 v[74:77], v[168:171], v[224:227], v[74:77]
	s_barrier
	s_add_i32 s71, 0, 0x14000
	v_add_u32_e32 v176, s71, v145
	s_add_i32 s42, s70, s56
	ds_read_b128 v[228:231], v176
	ds_read_b128 v[232:235], v176 offset:1024
	ds_read_b128 v[236:239], v176 offset:2048
	ds_read_b128 v[240:243], v176 offset:3072
	v_lshl_add_u64 v[176:177], s[4:5], 0, v[0:1]
	s_mov_b32 m0, s42
	v_lshl_add_u64 v[196:197], s[4:5], 0, v[134:135]
	global_load_lds_dwordx4 v[176:177], off
	s_add_i32 m0, s42, 0x2000
	s_nop 0
	global_load_lds_dwordx4 v[196:197], off
	s_waitcnt vmcnt(10)
	s_barrier
	s_waitcnt lgkmcnt(0)
	s_waitcnt lgkmcnt(0)
	v_mfma_f32_16x16x32_bf16 v[118:121], v[228:231], v[172:175], v[118:121]
	v_mfma_f32_16x16x32_bf16 v[114:117], v[236:239], v[172:175], v[114:117]
	v_mfma_f32_16x16x32_bf16 v[102:105], v[228:231], v[184:187], v[102:105]
	v_mfma_f32_16x16x32_bf16 v[98:101], v[236:239], v[184:187], v[98:101]
	v_mfma_f32_16x16x32_bf16 v[86:89], v[228:231], v[192:195], v[86:89]
	v_mfma_f32_16x16x32_bf16 v[82:85], v[236:239], v[192:195], v[82:85]
	v_mfma_f32_16x16x32_bf16 v[70:73], v[228:231], v[220:223], v[70:73]
	v_mfma_f32_16x16x32_bf16 v[66:69], v[236:239], v[220:223], v[66:69]
	v_mfma_f32_16x16x32_bf16 v[118:121], v[232:235], v[180:183], v[118:121]
	v_mfma_f32_16x16x32_bf16 v[114:117], v[240:243], v[180:183], v[114:117]
	v_mfma_f32_16x16x32_bf16 v[102:105], v[232:235], v[188:191], v[102:105]
	v_mfma_f32_16x16x32_bf16 v[98:101], v[240:243], v[188:191], v[98:101]
	v_mfma_f32_16x16x32_bf16 v[86:89], v[232:235], v[216:219], v[86:89]
	v_mfma_f32_16x16x32_bf16 v[82:85], v[240:243], v[216:219], v[82:85]
	v_mfma_f32_16x16x32_bf16 v[70:73], v[232:235], v[224:227], v[70:73]
	v_mfma_f32_16x16x32_bf16 v[66:69], v[240:243], v[224:227], v[66:69]
	s_mov_b32 m0, s39
	v_lshl_add_u64 v[200:201], s[44:45], 0, v[130:131]
	s_barrier
	ds_read_b128 v[172:175], v147 offset:16384
	ds_read_b128 v[180:183], v147 offset:17408
	ds_read_b128 v[184:187], v147 offset:18432
	ds_read_b128 v[188:191], v147 offset:19456
	ds_read_b128 v[192:195], v147 offset:20480
	ds_read_b128 v[216:219], v147 offset:21504
	ds_read_b128 v[220:223], v147 offset:22528
	ds_read_b128 v[224:227], v147 offset:23552
	global_load_lds_dwordx4 v[200:201], off
	v_lshl_add_u64 v[206:207], s[44:45], 0, v[132:133]
	s_mov_b32 m0, s59
	s_nop 0
	global_load_lds_dwordx4 v[206:207], off
	s_barrier
	s_waitcnt lgkmcnt(0)
	s_waitcnt lgkmcnt(0)
	v_mfma_f32_16x16x32_bf16 v[62:65], v[156:159], v[172:175], v[62:65]
	v_mfma_f32_16x16x32_bf16 v[58:61], v[164:167], v[172:175], v[58:61]
	v_mfma_f32_16x16x32_bf16 v[46:49], v[156:159], v[184:187], v[46:49]
	v_mfma_f32_16x16x32_bf16 v[42:45], v[164:167], v[184:187], v[42:45]
	v_mfma_f32_16x16x32_bf16 v[30:33], v[156:159], v[192:195], v[30:33]
	v_mfma_f32_16x16x32_bf16 v[26:29], v[164:167], v[192:195], v[26:29]
	v_mfma_f32_16x16x32_bf16 v[14:17], v[156:159], v[220:223], v[14:17]
	v_mfma_f32_16x16x32_bf16 v[10:13], v[164:167], v[220:223], v[10:13]
	v_mfma_f32_16x16x32_bf16 v[62:65], v[160:163], v[180:183], v[62:65]
	v_mfma_f32_16x16x32_bf16 v[58:61], v[168:171], v[180:183], v[58:61]
	v_mfma_f32_16x16x32_bf16 v[46:49], v[160:163], v[188:191], v[46:49]
	v_mfma_f32_16x16x32_bf16 v[42:45], v[168:171], v[188:191], v[42:45]
	v_mfma_f32_16x16x32_bf16 v[30:33], v[160:163], v[216:219], v[30:33]
	v_mfma_f32_16x16x32_bf16 v[26:29], v[168:171], v[216:219], v[26:29]
	v_mfma_f32_16x16x32_bf16 v[14:17], v[160:163], v[224:227], v[14:17]
	v_mfma_f32_16x16x32_bf16 v[10:13], v[168:171], v[224:227], v[10:13]
	s_barrier
	s_add_u32 s42, s4, 0x80000
	s_addc_u32 s43, s5, 0
	s_add_i32 s70, s71, s56
	v_lshl_add_u64 v[156:157], s[42:43], 0, v[0:1]
	s_mov_b32 m0, s70
	s_nop 0
	global_load_lds_dwordx4 v[156:157], off
	v_lshl_add_u64 v[156:157], s[42:43], 0, v[134:135]
	s_add_i32 m0, s70, 0x2000
	s_nop 0
	global_load_lds_dwordx4 v[156:157], off
	s_waitcnt vmcnt(10)
	s_barrier
	v_mfma_f32_16x16x32_bf16 v[54:57], v[228:231], v[172:175], v[54:57]
	v_mfma_f32_16x16x32_bf16 v[50:53], v[236:239], v[172:175], v[50:53]
	v_mfma_f32_16x16x32_bf16 v[38:41], v[228:231], v[184:187], v[38:41]
	v_mfma_f32_16x16x32_bf16 v[34:37], v[236:239], v[184:187], v[34:37]
	v_mfma_f32_16x16x32_bf16 v[22:25], v[228:231], v[192:195], v[22:25]
	v_mfma_f32_16x16x32_bf16 v[18:21], v[236:239], v[192:195], v[18:21]
	v_mfma_f32_16x16x32_bf16 v[6:9], v[228:231], v[220:223], v[6:9]
	v_mfma_f32_16x16x32_bf16 v[2:5], v[236:239], v[220:223], v[2:5]
	v_mfma_f32_16x16x32_bf16 v[54:57], v[232:235], v[180:183], v[54:57]
	v_mfma_f32_16x16x32_bf16 v[50:53], v[240:243], v[180:183], v[50:53]
	v_mfma_f32_16x16x32_bf16 v[38:41], v[232:235], v[188:191], v[38:41]
	v_mfma_f32_16x16x32_bf16 v[34:37], v[240:243], v[188:191], v[34:37]
	v_mfma_f32_16x16x32_bf16 v[22:25], v[232:235], v[216:219], v[22:25]
	v_mfma_f32_16x16x32_bf16 v[18:21], v[240:243], v[216:219], v[18:21]
	v_mfma_f32_16x16x32_bf16 v[6:9], v[232:235], v[224:227], v[6:9]
	v_mfma_f32_16x16x32_bf16 v[2:5], v[240:243], v[224:227], v[2:5]
	s_add_i32 s70, 0, 0x18000
	v_add_u32_e32 v168, s70, v145
	s_barrier
	ds_read_b128 v[156:159], v168
	ds_read_b128 v[160:163], v168 offset:1024
	ds_read_b128 v[164:167], v168 offset:2048
	ds_read_b128 v[168:171], v168 offset:3072
	s_add_u32 s42, s44, 0x80000
	s_addc_u32 s43, s45, 0
	s_mov_b32 m0, s60
	v_lshl_add_u64 v[208:209], s[42:43], 0, v[130:131]
	ds_read_b128 v[172:175], v147 offset:32768
	ds_read_b128 v[180:183], v147 offset:33792
	ds_read_b128 v[184:187], v147 offset:34816
	ds_read_b128 v[188:191], v147 offset:35840
	ds_read_b128 v[192:195], v147 offset:36864
	ds_read_b128 v[216:219], v147 offset:37888
	ds_read_b128 v[220:223], v147 offset:38912
	ds_read_b128 v[224:227], v147 offset:39936
	global_load_lds_dwordx4 v[208:209], off
	v_lshl_add_u64 v[208:209], s[42:43], 0, v[132:133]
	s_mov_b32 m0, s61
	s_nop 0
	global_load_lds_dwordx4 v[208:209], off
	s_waitcnt lgkmcnt(8)
	s_waitcnt vmcnt(10)
	s_barrier
	s_waitcnt lgkmcnt(0)
	s_waitcnt lgkmcnt(0)
	v_mfma_f32_16x16x32_bf16 v[126:129], v[156:159], v[172:175], v[126:129]
	v_mfma_f32_16x16x32_bf16 v[122:125], v[164:167], v[172:175], v[122:125]
	v_mfma_f32_16x16x32_bf16 v[110:113], v[156:159], v[184:187], v[110:113]
	v_mfma_f32_16x16x32_bf16 v[106:109], v[164:167], v[184:187], v[106:109]
	v_mfma_f32_16x16x32_bf16 v[94:97], v[156:159], v[192:195], v[94:97]
	v_mfma_f32_16x16x32_bf16 v[90:93], v[164:167], v[192:195], v[90:93]
	v_mfma_f32_16x16x32_bf16 v[78:81], v[156:159], v[220:223], v[78:81]
	v_mfma_f32_16x16x32_bf16 v[74:77], v[164:167], v[220:223], v[74:77]
	v_mfma_f32_16x16x32_bf16 v[126:129], v[160:163], v[180:183], v[126:129]
	v_mfma_f32_16x16x32_bf16 v[122:125], v[168:171], v[180:183], v[122:125]
	v_mfma_f32_16x16x32_bf16 v[110:113], v[160:163], v[188:191], v[110:113]
	v_mfma_f32_16x16x32_bf16 v[106:109], v[168:171], v[188:191], v[106:109]
	v_mfma_f32_16x16x32_bf16 v[94:97], v[160:163], v[216:219], v[94:97]
	v_mfma_f32_16x16x32_bf16 v[90:93], v[168:171], v[216:219], v[90:93]
	v_mfma_f32_16x16x32_bf16 v[78:81], v[160:163], v[224:227], v[78:81]
	v_mfma_f32_16x16x32_bf16 v[74:77], v[168:171], v[224:227], v[74:77]
	s_barrier
	s_add_i32 s42, 0, 0x1c000
	s_add_i32 s43, s70, s56
	v_add_u32_e32 v179, s42, v145
	v_lshl_add_u64 v[176:177], v[176:177], 0, s[78:79]
	s_mov_b32 m0, s43
	ds_read_b128 v[228:231], v179
	ds_read_b128 v[232:235], v179 offset:1024
	ds_read_b128 v[236:239], v179 offset:2048
	ds_read_b128 v[240:243], v179 offset:3072
	global_load_lds_dwordx4 v[176:177], off
	v_lshl_add_u64 v[176:177], v[196:197], 0, s[78:79]
	s_add_i32 m0, s43, 0x2000
	s_nop 0
	global_load_lds_dwordx4 v[176:177], off
	s_waitcnt vmcnt(10)
	s_barrier
	s_waitcnt lgkmcnt(0)
	s_waitcnt lgkmcnt(0)
	v_mfma_f32_16x16x32_bf16 v[118:121], v[228:231], v[172:175], v[118:121]
	v_mfma_f32_16x16x32_bf16 v[114:117], v[236:239], v[172:175], v[114:117]
	v_mfma_f32_16x16x32_bf16 v[102:105], v[228:231], v[184:187], v[102:105]
	v_mfma_f32_16x16x32_bf16 v[98:101], v[236:239], v[184:187], v[98:101]
	v_mfma_f32_16x16x32_bf16 v[86:89], v[228:231], v[192:195], v[86:89]
	v_mfma_f32_16x16x32_bf16 v[82:85], v[236:239], v[192:195], v[82:85]
	v_mfma_f32_16x16x32_bf16 v[70:73], v[228:231], v[220:223], v[70:73]
	v_mfma_f32_16x16x32_bf16 v[66:69], v[236:239], v[220:223], v[66:69]
	v_mfma_f32_16x16x32_bf16 v[118:121], v[232:235], v[180:183], v[118:121]
	v_mfma_f32_16x16x32_bf16 v[114:117], v[240:243], v[180:183], v[114:117]
	v_mfma_f32_16x16x32_bf16 v[102:105], v[232:235], v[188:191], v[102:105]
	v_mfma_f32_16x16x32_bf16 v[98:101], v[240:243], v[188:191], v[98:101]
	v_mfma_f32_16x16x32_bf16 v[86:89], v[232:235], v[216:219], v[86:89]
	v_mfma_f32_16x16x32_bf16 v[82:85], v[240:243], v[216:219], v[82:85]
	v_mfma_f32_16x16x32_bf16 v[70:73], v[232:235], v[224:227], v[70:73]
	v_mfma_f32_16x16x32_bf16 v[66:69], v[240:243], v[224:227], v[66:69]
	s_mov_b32 m0, s62
	v_lshl_add_u64 v[176:177], v[200:201], 0, s[78:79]
	s_barrier
	ds_read_b128 v[172:175], v147 offset:49152
	ds_read_b128 v[180:183], v147 offset:50176
	ds_read_b128 v[184:187], v147 offset:51200
	ds_read_b128 v[188:191], v147 offset:52224
	ds_read_b128 v[192:195], v147 offset:53248
	ds_read_b128 v[216:219], v147 offset:54272
	ds_read_b128 v[220:223], v147 offset:55296
	ds_read_b128 v[224:227], v147 offset:56320
	global_load_lds_dwordx4 v[176:177], off
	v_lshl_add_u64 v[176:177], v[206:207], 0, s[78:79]
	s_mov_b32 m0, s63
	s_nop 0
	global_load_lds_dwordx4 v[176:177], off
	s_barrier
	s_waitcnt lgkmcnt(0)
	s_waitcnt lgkmcnt(0)
	v_mfma_f32_16x16x32_bf16 v[62:65], v[156:159], v[172:175], v[62:65]
	v_mfma_f32_16x16x32_bf16 v[58:61], v[164:167], v[172:175], v[58:61]
	v_mfma_f32_16x16x32_bf16 v[46:49], v[156:159], v[184:187], v[46:49]
	v_mfma_f32_16x16x32_bf16 v[42:45], v[164:167], v[184:187], v[42:45]
	v_mfma_f32_16x16x32_bf16 v[30:33], v[156:159], v[192:195], v[30:33]
	v_mfma_f32_16x16x32_bf16 v[26:29], v[164:167], v[192:195], v[26:29]
	v_mfma_f32_16x16x32_bf16 v[14:17], v[156:159], v[220:223], v[14:17]
	v_mfma_f32_16x16x32_bf16 v[10:13], v[164:167], v[220:223], v[10:13]
	v_mfma_f32_16x16x32_bf16 v[62:65], v[160:163], v[180:183], v[62:65]
	v_mfma_f32_16x16x32_bf16 v[58:61], v[168:171], v[180:183], v[58:61]
	v_mfma_f32_16x16x32_bf16 v[46:49], v[160:163], v[188:191], v[46:49]
	v_mfma_f32_16x16x32_bf16 v[42:45], v[168:171], v[188:191], v[42:45]
	v_mfma_f32_16x16x32_bf16 v[30:33], v[160:163], v[216:219], v[30:33]
	v_mfma_f32_16x16x32_bf16 v[26:29], v[168:171], v[216:219], v[26:29]
	v_mfma_f32_16x16x32_bf16 v[14:17], v[160:163], v[224:227], v[14:17]
	v_mfma_f32_16x16x32_bf16 v[10:13], v[168:171], v[224:227], v[10:13]
	s_barrier
	s_add_u32 s4, s4, 0x80080
	s_addc_u32 s5, s5, 0
	s_add_i32 s42, s42, s56
	v_lshl_add_u64 v[156:157], s[4:5], 0, v[0:1]
	s_mov_b32 m0, s42
	s_nop 0
	global_load_lds_dwordx4 v[156:157], off
	v_lshl_add_u64 v[156:157], s[4:5], 0, v[134:135]
	s_add_i32 m0, s42, 0x2000
	s_nop 0
	global_load_lds_dwordx4 v[156:157], off
	s_waitcnt vmcnt(10)
	s_barrier
	v_mfma_f32_16x16x32_bf16 v[54:57], v[228:231], v[172:175], v[54:57]
	v_mfma_f32_16x16x32_bf16 v[50:53], v[236:239], v[172:175], v[50:53]
	v_mfma_f32_16x16x32_bf16 v[38:41], v[228:231], v[184:187], v[38:41]
	v_mfma_f32_16x16x32_bf16 v[34:37], v[236:239], v[184:187], v[34:37]
	v_mfma_f32_16x16x32_bf16 v[22:25], v[228:231], v[192:195], v[22:25]
	v_mfma_f32_16x16x32_bf16 v[18:21], v[236:239], v[192:195], v[18:21]
	v_mfma_f32_16x16x32_bf16 v[6:9], v[228:231], v[220:223], v[6:9]
	v_mfma_f32_16x16x32_bf16 v[2:5], v[236:239], v[220:223], v[2:5]
	v_mfma_f32_16x16x32_bf16 v[54:57], v[232:235], v[180:183], v[54:57]
	v_mfma_f32_16x16x32_bf16 v[50:53], v[240:243], v[180:183], v[50:53]
	v_mfma_f32_16x16x32_bf16 v[38:41], v[232:235], v[188:191], v[38:41]
	v_mfma_f32_16x16x32_bf16 v[34:37], v[240:243], v[188:191], v[34:37]
	v_mfma_f32_16x16x32_bf16 v[22:25], v[232:235], v[216:219], v[22:25]
	v_mfma_f32_16x16x32_bf16 v[18:21], v[240:243], v[216:219], v[18:21]
	v_mfma_f32_16x16x32_bf16 v[6:9], v[232:235], v[224:227], v[6:9]
	v_mfma_f32_16x16x32_bf16 v[2:5], v[240:243], v[224:227], v[2:5]
	s_add_i32 s69, s69, 2
	s_add_u32 s40, s40, 0x100
	s_addc_u32 s41, s41, 0
	s_add_u32 s67, s67, 0x100
	s_addc_u32 s68, s68, 0
	s_cmp_gt_u32 s69, 29
	s_barrier
	s_cbranch_scc1 .LBB0_200

.LBB0_847:
	s_add_u32 s24, s20, 0xfffe0080
	s_addc_u32 s25, s21, -1
	s_add_i32 s53, 0, 0x10000
	v_add_u32_e32 v140, s53, v143
	ds_read_b128 v[146:149], v140
	ds_read_b128 v[150:153], v140 offset:1024
	ds_read_b128 v[154:157], v140 offset:2048
	ds_read_b128 v[158:161], v140 offset:3072
	s_cmp_eq_u32 s52, 4
	s_cselect_b32 s27, s11, s25
	s_cselect_b32 s26, s48, s24
	s_cselect_b32 s25, s9, s51
	s_cselect_b32 s24, s49, s50
	v_lshl_add_u64 v[140:141], s[20:21], 0, v[136:137]
	s_add_i32 m0, s15, 0xc000
	ds_read_b128 v[162:165], v145
	ds_read_b128 v[166:169], v145 offset:1024
	ds_read_b128 v[170:173], v145 offset:2048
	ds_read_b128 v[174:177], v145 offset:3072
	ds_read_b128 v[180:183], v145 offset:4096
	ds_read_b128 v[184:187], v145 offset:5120
	ds_read_b128 v[188:191], v145 offset:6144
	ds_read_b128 v[192:195], v145 offset:7168
	global_load_lds_dwordx4 v[140:141], off
	v_lshl_add_u64 v[140:141], s[20:21], 0, v[138:139]
	s_add_i32 m0, s15, 0xe000
	s_nop 0
	global_load_lds_dwordx4 v[140:141], off
	s_waitcnt lgkmcnt(8)
	s_waitcnt vmcnt(10)
	s_barrier
	s_waitcnt lgkmcnt(0)
	s_waitcnt lgkmcnt(0)
	v_mfma_f32_16x16x32_bf16 v[126:129], v[146:149], v[162:165], v[126:129]
	v_mfma_f32_16x16x32_bf16 v[122:125], v[154:157], v[162:165], v[122:125]
	v_mfma_f32_16x16x32_bf16 v[118:121], v[146:149], v[170:173], v[118:121]
	v_mfma_f32_16x16x32_bf16 v[110:113], v[154:157], v[170:173], v[110:113]
	v_mfma_f32_16x16x32_bf16 v[102:105], v[146:149], v[180:183], v[102:105]
	v_mfma_f32_16x16x32_bf16 v[94:97], v[154:157], v[180:183], v[94:97]
	v_mfma_f32_16x16x32_bf16 v[86:89], v[146:149], v[188:191], v[86:89]
	v_mfma_f32_16x16x32_bf16 v[78:81], v[154:157], v[188:191], v[78:81]
	v_mfma_f32_16x16x32_bf16 v[126:129], v[150:153], v[166:169], v[126:129]
	v_mfma_f32_16x16x32_bf16 v[122:125], v[158:161], v[166:169], v[122:125]
	v_mfma_f32_16x16x32_bf16 v[118:121], v[150:153], v[174:177], v[118:121]
	v_mfma_f32_16x16x32_bf16 v[110:113], v[158:161], v[174:177], v[110:113]
	v_mfma_f32_16x16x32_bf16 v[102:105], v[150:153], v[184:187], v[102:105]
	v_mfma_f32_16x16x32_bf16 v[94:97], v[158:161], v[184:187], v[94:97]
	v_mfma_f32_16x16x32_bf16 v[86:89], v[150:153], v[192:195], v[86:89]
	v_mfma_f32_16x16x32_bf16 v[78:81], v[158:161], v[192:195], v[78:81]
	s_barrier
	s_add_i32 s56, 0, 0x14000
	v_add_u32_e32 v140, s56, v143
	s_add_i32 s53, s53, s36
	ds_read_b128 v[216:219], v140
	ds_read_b128 v[220:223], v140 offset:1024
	ds_read_b128 v[224:227], v140 offset:2048
	ds_read_b128 v[228:231], v140 offset:3072
	v_lshl_add_u64 v[140:141], s[24:25], 0, v[0:1]
	s_mov_b32 m0, s53
	v_lshl_add_u64 v[196:197], s[24:25], 0, v[130:131]
	global_load_lds_dwordx4 v[140:141], off
	s_add_i32 m0, s53, 0x2000
	s_nop 0
	global_load_lds_dwordx4 v[196:197], off
	s_waitcnt vmcnt(10)
	s_barrier
	s_waitcnt lgkmcnt(0)
	s_waitcnt lgkmcnt(0)
	v_mfma_f32_16x16x32_bf16 v[114:117], v[216:219], v[162:165], v[114:117]
	v_mfma_f32_16x16x32_bf16 v[106:109], v[224:227], v[162:165], v[106:109]
	v_mfma_f32_16x16x32_bf16 v[98:101], v[216:219], v[170:173], v[98:101]
	v_mfma_f32_16x16x32_bf16 v[90:93], v[224:227], v[170:173], v[90:93]
	v_mfma_f32_16x16x32_bf16 v[82:85], v[216:219], v[180:183], v[82:85]
	v_mfma_f32_16x16x32_bf16 v[74:77], v[224:227], v[180:183], v[74:77]
	v_mfma_f32_16x16x32_bf16 v[70:73], v[216:219], v[188:191], v[70:73]
	v_mfma_f32_16x16x32_bf16 v[66:69], v[224:227], v[188:191], v[66:69]
	v_mfma_f32_16x16x32_bf16 v[114:117], v[220:223], v[166:169], v[114:117]
	v_mfma_f32_16x16x32_bf16 v[106:109], v[228:231], v[166:169], v[106:109]
	v_mfma_f32_16x16x32_bf16 v[98:101], v[220:223], v[174:177], v[98:101]
	v_mfma_f32_16x16x32_bf16 v[90:93], v[228:231], v[174:177], v[90:93]
	v_mfma_f32_16x16x32_bf16 v[82:85], v[220:223], v[184:187], v[82:85]
	v_mfma_f32_16x16x32_bf16 v[74:77], v[228:231], v[184:187], v[74:77]
	v_mfma_f32_16x16x32_bf16 v[70:73], v[220:223], v[192:195], v[70:73]
	v_mfma_f32_16x16x32_bf16 v[66:69], v[228:231], v[192:195], v[66:69]
	s_mov_b32 m0, s15
	v_lshl_add_u64 v[200:201], s[26:27], 0, v[134:135]
	s_barrier
	ds_read_b128 v[162:165], v145 offset:16384
	ds_read_b128 v[166:169], v145 offset:17408
	ds_read_b128 v[170:173], v145 offset:18432
	ds_read_b128 v[174:177], v145 offset:19456
	ds_read_b128 v[180:183], v145 offset:20480
	ds_read_b128 v[184:187], v145 offset:21504
	ds_read_b128 v[188:191], v145 offset:22528
	ds_read_b128 v[192:195], v145 offset:23552
	global_load_lds_dwordx4 v[200:201], off
	v_lshl_add_u64 v[206:207], s[26:27], 0, v[132:133]
	s_mov_b32 m0, s40
	s_nop 0
	global_load_lds_dwordx4 v[206:207], off
	s_barrier
	s_waitcnt lgkmcnt(0)
	s_waitcnt lgkmcnt(0)
	v_mfma_f32_16x16x32_bf16 v[62:65], v[146:149], v[162:165], v[62:65]
	v_mfma_f32_16x16x32_bf16 v[58:61], v[154:157], v[162:165], v[58:61]
	v_mfma_f32_16x16x32_bf16 v[54:57], v[146:149], v[170:173], v[54:57]
	v_mfma_f32_16x16x32_bf16 v[46:49], v[154:157], v[170:173], v[46:49]
	v_mfma_f32_16x16x32_bf16 v[38:41], v[146:149], v[180:183], v[38:41]
	v_mfma_f32_16x16x32_bf16 v[30:33], v[154:157], v[180:183], v[30:33]
	v_mfma_f32_16x16x32_bf16 v[22:25], v[146:149], v[188:191], v[22:25]
	v_mfma_f32_16x16x32_bf16 v[14:17], v[154:157], v[188:191], v[14:17]
	v_mfma_f32_16x16x32_bf16 v[62:65], v[150:153], v[166:169], v[62:65]
	v_mfma_f32_16x16x32_bf16 v[58:61], v[158:161], v[166:169], v[58:61]
	v_mfma_f32_16x16x32_bf16 v[54:57], v[150:153], v[174:177], v[54:57]
	v_mfma_f32_16x16x32_bf16 v[46:49], v[158:161], v[174:177], v[46:49]
	v_mfma_f32_16x16x32_bf16 v[38:41], v[150:153], v[184:187], v[38:41]
	v_mfma_f32_16x16x32_bf16 v[30:33], v[158:161], v[184:187], v[30:33]
	v_mfma_f32_16x16x32_bf16 v[22:25], v[150:153], v[192:195], v[22:25]
	v_mfma_f32_16x16x32_bf16 v[14:17], v[158:161], v[192:195], v[14:17]
	s_barrier
	s_add_u32 s54, s24, 0x20000
	s_addc_u32 s55, s25, 0
	s_add_i32 s53, s56, s36
	v_lshl_add_u64 v[146:147], s[54:55], 0, v[0:1]
	s_mov_b32 m0, s53
	s_nop 0
	global_load_lds_dwordx4 v[146:147], off
	v_lshl_add_u64 v[146:147], s[54:55], 0, v[130:131]
	s_add_i32 m0, s53, 0x2000
	s_nop 0
	global_load_lds_dwordx4 v[146:147], off
	s_waitcnt vmcnt(10)
	s_barrier
	v_mfma_f32_16x16x32_bf16 v[50:53], v[216:219], v[162:165], v[50:53]
	v_mfma_f32_16x16x32_bf16 v[42:45], v[224:227], v[162:165], v[42:45]
	v_mfma_f32_16x16x32_bf16 v[34:37], v[216:219], v[170:173], v[34:37]
	v_mfma_f32_16x16x32_bf16 v[26:29], v[224:227], v[170:173], v[26:29]
	v_mfma_f32_16x16x32_bf16 v[18:21], v[216:219], v[180:183], v[18:21]
	v_mfma_f32_16x16x32_bf16 v[10:13], v[224:227], v[180:183], v[10:13]
	v_mfma_f32_16x16x32_bf16 v[6:9], v[216:219], v[188:191], v[6:9]
	v_mfma_f32_16x16x32_bf16 v[2:5], v[224:227], v[188:191], v[2:5]
	v_mfma_f32_16x16x32_bf16 v[50:53], v[220:223], v[166:169], v[50:53]
	v_mfma_f32_16x16x32_bf16 v[42:45], v[228:231], v[166:169], v[42:45]
	v_mfma_f32_16x16x32_bf16 v[34:37], v[220:223], v[174:177], v[34:37]
	v_mfma_f32_16x16x32_bf16 v[26:29], v[228:231], v[174:177], v[26:29]
	v_mfma_f32_16x16x32_bf16 v[18:21], v[220:223], v[184:187], v[18:21]
	v_mfma_f32_16x16x32_bf16 v[10:13], v[228:231], v[184:187], v[10:13]
	v_mfma_f32_16x16x32_bf16 v[6:9], v[220:223], v[192:195], v[6:9]
	v_mfma_f32_16x16x32_bf16 v[2:5], v[228:231], v[192:195], v[2:5]
	s_add_i32 s53, 0, 0x18000
	v_add_u32_e32 v158, s53, v143
	s_barrier
	ds_read_b128 v[146:149], v158
	ds_read_b128 v[150:153], v158 offset:1024
	ds_read_b128 v[154:157], v158 offset:2048
	ds_read_b128 v[158:161], v158 offset:3072
	s_add_u32 s26, s26, 0x20000
	s_addc_u32 s27, s27, 0
	s_mov_b32 m0, s41
	v_lshl_add_u64 v[208:209], s[26:27], 0, v[134:135]
	ds_read_b128 v[162:165], v145 offset:32768
	ds_read_b128 v[166:169], v145 offset:33792
	ds_read_b128 v[170:173], v145 offset:34816
	ds_read_b128 v[174:177], v145 offset:35840
	ds_read_b128 v[180:183], v145 offset:36864
	ds_read_b128 v[184:187], v145 offset:37888
	ds_read_b128 v[188:191], v145 offset:38912
	ds_read_b128 v[192:195], v145 offset:39936
	global_load_lds_dwordx4 v[208:209], off
	v_lshl_add_u64 v[208:209], s[26:27], 0, v[132:133]
	s_mov_b32 m0, s42
	s_nop 0
	global_load_lds_dwordx4 v[208:209], off
	s_waitcnt lgkmcnt(8)
	s_waitcnt vmcnt(10)
	s_barrier
	s_waitcnt lgkmcnt(0)
	s_waitcnt lgkmcnt(0)
	v_mfma_f32_16x16x32_bf16 v[126:129], v[146:149], v[162:165], v[126:129]
	v_mfma_f32_16x16x32_bf16 v[122:125], v[154:157], v[162:165], v[122:125]
	v_mfma_f32_16x16x32_bf16 v[118:121], v[146:149], v[170:173], v[118:121]
	v_mfma_f32_16x16x32_bf16 v[110:113], v[154:157], v[170:173], v[110:113]
	v_mfma_f32_16x16x32_bf16 v[102:105], v[146:149], v[180:183], v[102:105]
	v_mfma_f32_16x16x32_bf16 v[94:97], v[154:157], v[180:183], v[94:97]
	v_mfma_f32_16x16x32_bf16 v[86:89], v[146:149], v[188:191], v[86:89]
	v_mfma_f32_16x16x32_bf16 v[78:81], v[154:157], v[188:191], v[78:81]
	v_mfma_f32_16x16x32_bf16 v[126:129], v[150:153], v[166:169], v[126:129]
	v_mfma_f32_16x16x32_bf16 v[122:125], v[158:161], v[166:169], v[122:125]
	v_mfma_f32_16x16x32_bf16 v[118:121], v[150:153], v[174:177], v[118:121]
	v_mfma_f32_16x16x32_bf16 v[110:113], v[158:161], v[174:177], v[110:113]
	v_mfma_f32_16x16x32_bf16 v[102:105], v[150:153], v[184:187], v[102:105]
	v_mfma_f32_16x16x32_bf16 v[94:97], v[158:161], v[184:187], v[94:97]
	v_mfma_f32_16x16x32_bf16 v[86:89], v[150:153], v[192:195], v[86:89]
	v_mfma_f32_16x16x32_bf16 v[78:81], v[158:161], v[192:195], v[78:81]
	s_barrier
	s_add_i32 s26, 0, 0x1c000
	s_add_i32 s27, s53, s36
	v_add_u32_e32 v179, s26, v143
	v_lshl_add_u64 v[140:141], v[140:141], 0, s[78:79]
	s_mov_b32 m0, s27
	ds_read_b128 v[216:219], v179
	ds_read_b128 v[220:223], v179 offset:1024
	ds_read_b128 v[224:227], v179 offset:2048
	ds_read_b128 v[228:231], v179 offset:3072
	global_load_lds_dwordx4 v[140:141], off
	v_lshl_add_u64 v[140:141], v[196:197], 0, s[78:79]
	s_add_i32 m0, s27, 0x2000
	s_nop 0
	global_load_lds_dwordx4 v[140:141], off
	s_waitcnt vmcnt(10)
	s_barrier
	s_waitcnt lgkmcnt(0)
	s_waitcnt lgkmcnt(0)
	v_mfma_f32_16x16x32_bf16 v[114:117], v[216:219], v[162:165], v[114:117]
	v_mfma_f32_16x16x32_bf16 v[106:109], v[224:227], v[162:165], v[106:109]
	v_mfma_f32_16x16x32_bf16 v[98:101], v[216:219], v[170:173], v[98:101]
	v_mfma_f32_16x16x32_bf16 v[90:93], v[224:227], v[170:173], v[90:93]
	v_mfma_f32_16x16x32_bf16 v[82:85], v[216:219], v[180:183], v[82:85]
	v_mfma_f32_16x16x32_bf16 v[74:77], v[224:227], v[180:183], v[74:77]
	v_mfma_f32_16x16x32_bf16 v[70:73], v[216:219], v[188:191], v[70:73]
	v_mfma_f32_16x16x32_bf16 v[66:69], v[224:227], v[188:191], v[66:69]
	v_mfma_f32_16x16x32_bf16 v[114:117], v[220:223], v[166:169], v[114:117]
	v_mfma_f32_16x16x32_bf16 v[106:109], v[228:231], v[166:169], v[106:109]
	v_mfma_f32_16x16x32_bf16 v[98:101], v[220:223], v[174:177], v[98:101]
	v_mfma_f32_16x16x32_bf16 v[90:93], v[228:231], v[174:177], v[90:93]
	v_mfma_f32_16x16x32_bf16 v[82:85], v[220:223], v[184:187], v[82:85]
	v_mfma_f32_16x16x32_bf16 v[74:77], v[228:231], v[184:187], v[74:77]
	v_mfma_f32_16x16x32_bf16 v[70:73], v[220:223], v[192:195], v[70:73]
	v_mfma_f32_16x16x32_bf16 v[66:69], v[228:231], v[192:195], v[66:69]
	s_mov_b32 m0, s45
	v_lshl_add_u64 v[140:141], v[200:201], 0, s[78:79]
	s_barrier
	ds_read_b128 v[162:165], v145 offset:49152
	ds_read_b128 v[166:169], v145 offset:50176
	ds_read_b128 v[170:173], v145 offset:51200
	ds_read_b128 v[174:177], v145 offset:52224
	ds_read_b128 v[180:183], v145 offset:53248
	ds_read_b128 v[184:187], v145 offset:54272
	ds_read_b128 v[188:191], v145 offset:55296
	ds_read_b128 v[192:195], v145 offset:56320
	global_load_lds_dwordx4 v[140:141], off
	v_lshl_add_u64 v[140:141], v[206:207], 0, s[78:79]
	s_mov_b32 m0, s46
	s_nop 0
	global_load_lds_dwordx4 v[140:141], off
	s_barrier
	s_waitcnt lgkmcnt(0)
	s_waitcnt lgkmcnt(0)
	v_mfma_f32_16x16x32_bf16 v[62:65], v[146:149], v[162:165], v[62:65]
	v_mfma_f32_16x16x32_bf16 v[58:61], v[154:157], v[162:165], v[58:61]
	v_mfma_f32_16x16x32_bf16 v[54:57], v[146:149], v[170:173], v[54:57]
	v_mfma_f32_16x16x32_bf16 v[46:49], v[154:157], v[170:173], v[46:49]
	v_mfma_f32_16x16x32_bf16 v[38:41], v[146:149], v[180:183], v[38:41]
	v_mfma_f32_16x16x32_bf16 v[30:33], v[154:157], v[180:183], v[30:33]
	v_mfma_f32_16x16x32_bf16 v[22:25], v[146:149], v[188:191], v[22:25]
	v_mfma_f32_16x16x32_bf16 v[14:17], v[154:157], v[188:191], v[14:17]
	v_mfma_f32_16x16x32_bf16 v[62:65], v[150:153], v[166:169], v[62:65]
	v_mfma_f32_16x16x32_bf16 v[58:61], v[158:161], v[166:169], v[58:61]
	v_mfma_f32_16x16x32_bf16 v[54:57], v[150:153], v[174:177], v[54:57]
	v_mfma_f32_16x16x32_bf16 v[46:49], v[158:161], v[174:177], v[46:49]
	v_mfma_f32_16x16x32_bf16 v[38:41], v[150:153], v[184:187], v[38:41]
	v_mfma_f32_16x16x32_bf16 v[30:33], v[158:161], v[184:187], v[30:33]
	v_mfma_f32_16x16x32_bf16 v[22:25], v[150:153], v[192:195], v[22:25]
	v_mfma_f32_16x16x32_bf16 v[14:17], v[158:161], v[192:195], v[14:17]
	s_barrier
	s_add_u32 s24, s24, 0x20080
	s_addc_u32 s25, s25, 0
	s_add_i32 s26, s26, s36
	v_lshl_add_u64 v[140:141], s[24:25], 0, v[0:1]
	s_mov_b32 m0, s26
	s_nop 0
	global_load_lds_dwordx4 v[140:141], off
	v_lshl_add_u64 v[140:141], s[24:25], 0, v[130:131]
	s_add_i32 m0, s26, 0x2000
	s_nop 0
	global_load_lds_dwordx4 v[140:141], off
	s_waitcnt vmcnt(10)
	s_barrier
	v_mfma_f32_16x16x32_bf16 v[50:53], v[216:219], v[162:165], v[50:53]
	v_mfma_f32_16x16x32_bf16 v[42:45], v[224:227], v[162:165], v[42:45]
	v_mfma_f32_16x16x32_bf16 v[34:37], v[216:219], v[170:173], v[34:37]
	v_mfma_f32_16x16x32_bf16 v[26:29], v[224:227], v[170:173], v[26:29]
	v_mfma_f32_16x16x32_bf16 v[18:21], v[216:219], v[180:183], v[18:21]
	v_mfma_f32_16x16x32_bf16 v[10:13], v[224:227], v[180:183], v[10:13]
	v_mfma_f32_16x16x32_bf16 v[6:9], v[216:219], v[188:191], v[6:9]
	v_mfma_f32_16x16x32_bf16 v[2:5], v[224:227], v[188:191], v[2:5]
	v_mfma_f32_16x16x32_bf16 v[50:53], v[220:223], v[166:169], v[50:53]
	v_mfma_f32_16x16x32_bf16 v[42:45], v[228:231], v[166:169], v[42:45]
	v_mfma_f32_16x16x32_bf16 v[34:37], v[220:223], v[174:177], v[34:37]
	v_mfma_f32_16x16x32_bf16 v[26:29], v[228:231], v[174:177], v[26:29]
	v_mfma_f32_16x16x32_bf16 v[18:21], v[220:223], v[184:187], v[18:21]
	v_mfma_f32_16x16x32_bf16 v[10:13], v[228:231], v[184:187], v[10:13]
	v_mfma_f32_16x16x32_bf16 v[6:9], v[220:223], v[192:195], v[6:9]
	v_mfma_f32_16x16x32_bf16 v[2:5], v[228:231], v[192:195], v[2:5]
	s_add_i32 s52, s52, 2
	s_add_u32 s20, s20, 0x100
	s_addc_u32 s21, s21, 0
	s_add_u32 s50, s50, 0x100
	s_addc_u32 s51, s51, 0
	s_cmp_gt_u32 s52, 5
	s_barrier
	s_cbranch_scc0 .LBB0_847
	v_lshl_add_u32 v148, s14, 8, v142
	v_lshl_or_b32 v140, s47, 8, v144
	v_ashrrev_i32_e32 v141, 31, v140
	v_mad_i64_i32 v[146:147], s[20:21], s44, v148, 0
	v_lshl_add_u64 v[146:147], v[146:147], 1, s[6:7]
	v_lshlrev_b64 v[140:141], 1, v[140:141]
	v_lshl_add_u64 v[146:147], v[146:147], 0, v[140:141]
	v_cvt_pk_bf16_f32 v126, v126, v127
	v_cvt_pk_bf16_f32 v127, v128, v129
	v_cvt_pk_bf16_f32 v128, v122, v123
	v_cvt_pk_bf16_f32 v129, v124, v125
	global_store_dwordx4 v[146:147], v[126:129], off
	v_cvt_pk_bf16_f32 v114, v114, v115
	v_cvt_pk_bf16_f32 v115, v116, v117
	v_cvt_pk_bf16_f32 v116, v106, v107
	v_or_b32_e32 v106, 16, v148
	v_mad_i64_i32 v[106:107], s[20:21], s44, v106, 0
	v_lshl_add_u64 v[106:107], v[106:107], 1, s[6:7]
	v_cvt_pk_bf16_f32 v117, v108, v109
	global_store_dwordx4 v[146:147], v[114:117], off offset:256
	s_and_b64 vcc, exec, s[0:1]
	s_mov_b32 s47, s8
	v_lshl_add_u64 v[114:115], v[106:107], 0, v[140:141]
	v_cvt_pk_bf16_f32 v106, v118, v119
	v_cvt_pk_bf16_f32 v107, v120, v121
	v_cvt_pk_bf16_f32 v108, v110, v111
	v_cvt_pk_bf16_f32 v109, v112, v113
	global_store_dwordx4 v[114:115], v[106:109], off
	v_cvt_pk_bf16_f32 v98, v98, v99
	v_cvt_pk_bf16_f32 v99, v100, v101
	v_cvt_pk_bf16_f32 v100, v90, v91
	v_or_b32_e32 v90, 32, v148
	v_mad_i64_i32 v[90:91], s[20:21], s44, v90, 0
	v_lshl_add_u64 v[90:91], v[90:91], 1, s[6:7]
	v_cvt_pk_bf16_f32 v101, v92, v93
	global_store_dwordx4 v[114:115], v[98:101], off offset:256
	s_mov_b32 s14, s10
	s_mov_b64 s[24:25], s[18:19]
	v_lshl_add_u64 v[98:99], v[90:91], 0, v[140:141]
	v_cvt_pk_bf16_f32 v90, v102, v103
	v_cvt_pk_bf16_f32 v91, v104, v105
	v_cvt_pk_bf16_f32 v92, v94, v95
	v_cvt_pk_bf16_f32 v93, v96, v97
	global_store_dwordx4 v[98:99], v[90:93], off
	v_cvt_pk_bf16_f32 v82, v82, v83
	v_cvt_pk_bf16_f32 v83, v84, v85
	v_cvt_pk_bf16_f32 v84, v74, v75
	v_or_b32_e32 v74, 48, v148
	v_mad_i64_i32 v[74:75], s[20:21], s44, v74, 0
	v_lshl_add_u64 v[74:75], v[74:75], 1, s[6:7]
	v_cvt_pk_bf16_f32 v85, v76, v77
	global_store_dwordx4 v[98:99], v[82:85], off offset:256
	s_nop 1
	v_lshl_add_u64 v[82:83], v[74:75], 0, v[140:141]
	v_cvt_pk_bf16_f32 v74, v86, v87
	v_cvt_pk_bf16_f32 v75, v88, v89
	v_cvt_pk_bf16_f32 v76, v78, v79
	v_cvt_pk_bf16_f32 v77, v80, v81
	global_store_dwordx4 v[82:83], v[74:77], off
	v_cvt_pk_bf16_f32 v70, v70, v71
	v_cvt_pk_bf16_f32 v71, v72, v73
	v_cvt_pk_bf16_f32 v72, v66, v67
	v_add_u32_e32 v66, 0x80, v148
	v_mad_i64_i32 v[66:67], s[20:21], s44, v66, 0
	v_lshl_add_u64 v[66:67], v[66:67], 1, s[6:7]
	v_lshl_add_u64 v[66:67], v[66:67], 0, v[140:141]
	v_cvt_pk_bf16_f32 v73, v68, v69
	global_store_dwordx4 v[82:83], v[70:73], off offset:256
	v_cvt_pk_bf16_f32 v62, v62, v63
	v_cvt_pk_bf16_f32 v63, v64, v65
	v_cvt_pk_bf16_f32 v64, v58, v59
	v_cvt_pk_bf16_f32 v65, v60, v61
	global_store_dwordx4 v[66:67], v[62:65], off
	v_cvt_pk_bf16_f32 v50, v50, v51
	v_cvt_pk_bf16_f32 v51, v52, v53
	v_cvt_pk_bf16_f32 v52, v42, v43
	v_add_u32_e32 v42, 0x90, v148
	v_mad_i64_i32 v[42:43], s[20:21], s44, v42, 0
	v_lshl_add_u64 v[42:43], v[42:43], 1, s[6:7]
	v_cvt_pk_bf16_f32 v53, v44, v45
	global_store_dwordx4 v[66:67], v[50:53], off offset:256
	s_nop 1
	v_lshl_add_u64 v[50:51], v[42:43], 0, v[140:141]
	v_cvt_pk_bf16_f32 v42, v54, v55
	v_cvt_pk_bf16_f32 v43, v56, v57
	v_cvt_pk_bf16_f32 v44, v46, v47
	v_cvt_pk_bf16_f32 v45, v48, v49
	global_store_dwordx4 v[50:51], v[42:45], off
	v_cvt_pk_bf16_f32 v34, v34, v35
	v_cvt_pk_bf16_f32 v35, v36, v37
	v_cvt_pk_bf16_f32 v36, v26, v27
	v_add_u32_e32 v26, 0xa0, v148
	v_mad_i64_i32 v[26:27], s[20:21], s44, v26, 0
	v_lshl_add_u64 v[26:27], v[26:27], 1, s[6:7]
	v_cvt_pk_bf16_f32 v37, v28, v29
	global_store_dwordx4 v[50:51], v[34:37], off offset:256
	s_nop 1
	v_lshl_add_u64 v[34:35], v[26:27], 0, v[140:141]
	v_cvt_pk_bf16_f32 v26, v38, v39
	v_cvt_pk_bf16_f32 v27, v40, v41
	v_cvt_pk_bf16_f32 v28, v30, v31
	v_cvt_pk_bf16_f32 v29, v32, v33
	global_store_dwordx4 v[34:35], v[26:29], off
	v_cvt_pk_bf16_f32 v18, v18, v19
	v_cvt_pk_bf16_f32 v19, v20, v21
	v_cvt_pk_bf16_f32 v20, v10, v11
	v_add_u32_e32 v10, 0xb0, v148
	v_mad_i64_i32 v[10:11], s[20:21], s44, v10, 0
	v_lshl_add_u64 v[10:11], v[10:11], 1, s[6:7]
	v_cvt_pk_bf16_f32 v21, v12, v13
	global_store_dwordx4 v[34:35], v[18:21], off offset:256
	s_mov_b64 s[20:21], s[16:17]
	s_nop 0
	v_lshl_add_u64 v[18:19], v[10:11], 0, v[140:141]
	v_cvt_pk_bf16_f32 v10, v22, v23
	v_cvt_pk_bf16_f32 v11, v24, v25
	v_cvt_pk_bf16_f32 v12, v14, v15
	v_cvt_pk_bf16_f32 v13, v16, v17
	global_store_dwordx4 v[18:19], v[10:13], off
	v_cvt_pk_bf16_f32 v6, v6, v7
	v_cvt_pk_bf16_f32 v7, v8, v9
	v_cvt_pk_bf16_f32 v8, v2, v3
	v_cvt_pk_bf16_f32 v9, v4, v5
	global_store_dwordx4 v[18:19], v[6:9], off offset:256
	s_cbranch_vccz .LBB0_844
	s_waitcnt vmcnt(0)
	s_cmpk_gt_u32 s28, 0xff
	s_cbranch_scc1 .LBB0_838
	s_barrier
	s_branch .LBB0_838

.LBB0_1348:
	s_add_i32 s40, s14, 2
	s_add_u32 s16, s12, 0x80
	s_addc_u32 s15, s13, 0
	s_add_i32 s41, 0, 0x10000
	v_add_u32_e32 v126, s41, v216
	ds_read_b128 v[114:117], v126
	ds_read_b128 v[118:121], v126 offset:1024
	ds_read_b128 v[122:125], v126 offset:2048
	ds_read_b128 v[126:129], v126 offset:3072
	s_cmp_eq_u32 s30, s14
	s_cselect_b32 s14, s4, s16
	s_cselect_b32 s15, s5, s15
	s_cselect_b32 s17, s7, s39
	s_cselect_b32 s16, s6, s38
	v_lshl_add_u64 v[186:187], s[12:13], 0, v[182:183]
	s_add_i32 m0, s23, 0xc000
	ds_read_b128 v[130:133], v218
	ds_read_b128 v[134:137], v218 offset:1024
	ds_read_b128 v[138:141], v218 offset:2048
	ds_read_b128 v[142:145], v218 offset:3072
	ds_read_b128 v[154:157], v218 offset:4096
	ds_read_b128 v[162:165], v218 offset:5120
	ds_read_b128 v[170:173], v218 offset:6144
	ds_read_b128 v[174:177], v218 offset:7168
	global_load_lds_dwordx4 v[186:187], off
	v_lshl_add_u64 v[186:187], s[12:13], 0, v[184:185]
	s_add_i32 m0, s23, 0xe000
	s_nop 0
	global_load_lds_dwordx4 v[186:187], off
	s_waitcnt lgkmcnt(8)
	s_waitcnt vmcnt(10)
	s_barrier
	s_waitcnt lgkmcnt(0)
	s_waitcnt lgkmcnt(0)
	v_mfma_f32_16x16x32_bf16 v[166:169], v[114:117], v[130:133], v[166:169]
	v_mfma_f32_16x16x32_bf16 v[158:161], v[122:125], v[130:133], v[158:161]
	v_mfma_f32_16x16x32_bf16 v[110:113], v[114:117], v[138:141], v[110:113]
	v_mfma_f32_16x16x32_bf16 v[106:109], v[122:125], v[138:141], v[106:109]
	v_mfma_f32_16x16x32_bf16 v[94:97], v[114:117], v[154:157], v[94:97]
	v_mfma_f32_16x16x32_bf16 v[90:93], v[122:125], v[154:157], v[90:93]
	v_mfma_f32_16x16x32_bf16 v[78:81], v[114:117], v[170:173], v[78:81]
	v_mfma_f32_16x16x32_bf16 v[74:77], v[122:125], v[170:173], v[74:77]
	v_mfma_f32_16x16x32_bf16 v[166:169], v[118:121], v[134:137], v[166:169]
	v_mfma_f32_16x16x32_bf16 v[158:161], v[126:129], v[134:137], v[158:161]
	v_mfma_f32_16x16x32_bf16 v[110:113], v[118:121], v[142:145], v[110:113]
	v_mfma_f32_16x16x32_bf16 v[106:109], v[126:129], v[142:145], v[106:109]
	v_mfma_f32_16x16x32_bf16 v[94:97], v[118:121], v[162:165], v[94:97]
	v_mfma_f32_16x16x32_bf16 v[90:93], v[126:129], v[162:165], v[90:93]
	v_mfma_f32_16x16x32_bf16 v[78:81], v[118:121], v[174:177], v[78:81]
	v_mfma_f32_16x16x32_bf16 v[74:77], v[126:129], v[174:177], v[74:77]
	s_barrier
	s_add_i32 s42, 0, 0x14000
	s_add_i32 s41, s41, s22
	v_add_u32_e32 v199, s42, v216
	v_lshl_add_u64 v[200:201], s[16:17], 0, v[0:1]
	s_mov_b32 m0, s41
	ds_read_b128 v[186:189], v199
	ds_read_b128 v[190:193], v199 offset:1024
	ds_read_b128 v[194:197], v199 offset:2048
	ds_read_b128 v[206:209], v199 offset:3072
	global_load_lds_dwordx4 v[200:201], off
	v_lshl_add_u64 v[220:221], s[16:17], 0, v[180:181]
	s_add_i32 m0, s41, 0x2000
	s_nop 0
	global_load_lds_dwordx4 v[220:221], off
	s_waitcnt vmcnt(10)
	s_barrier
	s_waitcnt lgkmcnt(0)
	s_waitcnt lgkmcnt(0)
	v_mfma_f32_16x16x32_bf16 v[150:153], v[186:189], v[130:133], v[150:153]
	v_mfma_f32_16x16x32_bf16 v[102:105], v[186:189], v[138:141], v[102:105]
	v_mfma_f32_16x16x32_bf16 v[98:101], v[194:197], v[138:141], v[98:101]
	v_mfma_f32_16x16x32_bf16 v[86:89], v[186:189], v[154:157], v[86:89]
	v_mfma_f32_16x16x32_bf16 v[82:85], v[194:197], v[154:157], v[82:85]
	v_mfma_f32_16x16x32_bf16 v[70:73], v[186:189], v[170:173], v[70:73]
	v_mfma_f32_16x16x32_bf16 v[66:69], v[194:197], v[170:173], v[66:69]
	v_mfma_f32_16x16x32_bf16 v[150:153], v[190:193], v[134:137], v[150:153]
	v_mfma_f32_16x16x32_bf16 v[130:133], v[194:197], v[130:133], v[146:149]
	v_mfma_f32_16x16x32_bf16 v[102:105], v[190:193], v[142:145], v[102:105]
	v_mfma_f32_16x16x32_bf16 v[98:101], v[206:209], v[142:145], v[98:101]
	v_mfma_f32_16x16x32_bf16 v[86:89], v[190:193], v[162:165], v[86:89]
	v_mfma_f32_16x16x32_bf16 v[82:85], v[206:209], v[162:165], v[82:85]
	v_mfma_f32_16x16x32_bf16 v[70:73], v[190:193], v[174:177], v[70:73]
	v_mfma_f32_16x16x32_bf16 v[66:69], v[206:209], v[174:177], v[66:69]
	v_mfma_f32_16x16x32_bf16 v[130:133], v[206:209], v[134:137], v[130:133]
	s_mov_b32 m0, s23
	v_lshl_add_u64 v[222:223], s[14:15], 0, v[0:1]
	s_barrier
	ds_read_b128 v[134:137], v218 offset:16384
	ds_read_b128 v[138:141], v218 offset:17408
	ds_read_b128 v[142:145], v218 offset:18432
	ds_read_b128 v[146:149], v218 offset:19456
	ds_read_b128 v[154:157], v218 offset:20480
	ds_read_b128 v[162:165], v218 offset:21504
	ds_read_b128 v[170:173], v218 offset:22528
	ds_read_b128 v[174:177], v218 offset:23552
	global_load_lds_dwordx4 v[222:223], off
	v_lshl_add_u64 v[224:225], s[14:15], 0, v[180:181]
	s_mov_b32 m0, s24
	s_nop 0
	global_load_lds_dwordx4 v[224:225], off
	s_barrier
	s_waitcnt lgkmcnt(0)
	s_waitcnt lgkmcnt(0)
	v_mfma_f32_16x16x32_bf16 v[62:65], v[114:117], v[134:137], v[62:65]
	v_mfma_f32_16x16x32_bf16 v[58:61], v[122:125], v[134:137], v[58:61]
	v_mfma_f32_16x16x32_bf16 v[46:49], v[114:117], v[142:145], v[46:49]
	v_mfma_f32_16x16x32_bf16 v[42:45], v[122:125], v[142:145], v[42:45]
	v_mfma_f32_16x16x32_bf16 v[30:33], v[114:117], v[154:157], v[30:33]
	v_mfma_f32_16x16x32_bf16 v[26:29], v[122:125], v[154:157], v[26:29]
	v_mfma_f32_16x16x32_bf16 v[14:17], v[114:117], v[170:173], v[14:17]
	v_mfma_f32_16x16x32_bf16 v[10:13], v[122:125], v[170:173], v[10:13]
	v_mfma_f32_16x16x32_bf16 v[62:65], v[118:121], v[138:141], v[62:65]
	v_mfma_f32_16x16x32_bf16 v[58:61], v[126:129], v[138:141], v[58:61]
	v_mfma_f32_16x16x32_bf16 v[46:49], v[118:121], v[146:149], v[46:49]
	v_mfma_f32_16x16x32_bf16 v[42:45], v[126:129], v[146:149], v[42:45]
	v_mfma_f32_16x16x32_bf16 v[30:33], v[118:121], v[162:165], v[30:33]
	v_mfma_f32_16x16x32_bf16 v[26:29], v[126:129], v[162:165], v[26:29]
	v_mfma_f32_16x16x32_bf16 v[14:17], v[118:121], v[174:177], v[14:17]
	v_mfma_f32_16x16x32_bf16 v[10:13], v[126:129], v[174:177], v[10:13]
	s_barrier
	s_add_u32 s16, s16, s2
	s_addc_u32 s17, s17, 0
	s_add_i32 s41, s42, s22
	v_lshl_add_u64 v[226:227], s[16:17], 0, v[0:1]
	s_mov_b32 m0, s41
	v_lshl_add_u64 v[228:229], s[16:17], 0, v[180:181]
	global_load_lds_dwordx4 v[226:227], off
	s_add_i32 m0, s41, 0x2000
	s_nop 0
	global_load_lds_dwordx4 v[228:229], off
	s_waitcnt vmcnt(10)
	s_barrier
	v_mfma_f32_16x16x32_bf16 v[54:57], v[186:189], v[134:137], v[54:57]
	v_mfma_f32_16x16x32_bf16 v[50:53], v[194:197], v[134:137], v[50:53]
	v_mfma_f32_16x16x32_bf16 v[38:41], v[186:189], v[142:145], v[38:41]
	v_mfma_f32_16x16x32_bf16 v[34:37], v[194:197], v[142:145], v[34:37]
	v_mfma_f32_16x16x32_bf16 v[22:25], v[186:189], v[154:157], v[22:25]
	v_mfma_f32_16x16x32_bf16 v[18:21], v[194:197], v[154:157], v[18:21]
	v_mfma_f32_16x16x32_bf16 v[6:9], v[186:189], v[170:173], v[6:9]
	v_mfma_f32_16x16x32_bf16 v[2:5], v[194:197], v[170:173], v[2:5]
	v_mfma_f32_16x16x32_bf16 v[54:57], v[190:193], v[138:141], v[54:57]
	v_mfma_f32_16x16x32_bf16 v[50:53], v[206:209], v[138:141], v[50:53]
	v_mfma_f32_16x16x32_bf16 v[38:41], v[190:193], v[146:149], v[38:41]
	v_mfma_f32_16x16x32_bf16 v[34:37], v[206:209], v[146:149], v[34:37]
	v_mfma_f32_16x16x32_bf16 v[22:25], v[190:193], v[162:165], v[22:25]
	v_mfma_f32_16x16x32_bf16 v[18:21], v[206:209], v[162:165], v[18:21]
	v_mfma_f32_16x16x32_bf16 v[6:9], v[190:193], v[174:177], v[6:9]
	v_mfma_f32_16x16x32_bf16 v[2:5], v[206:209], v[174:177], v[2:5]
	s_add_i32 s16, 0, 0x18000
	v_add_u32_e32 v126, s16, v216
	s_barrier
	ds_read_b128 v[114:117], v126
	ds_read_b128 v[118:121], v126 offset:1024
	ds_read_b128 v[122:125], v126 offset:2048
	ds_read_b128 v[126:129], v126 offset:3072
	s_add_u32 s14, s14, s2
	s_addc_u32 s15, s15, 0
	s_mov_b32 m0, s25
	v_lshl_add_u64 v[146:147], s[14:15], 0, v[0:1]
	ds_read_b128 v[134:137], v218 offset:32768
	ds_read_b128 v[138:141], v218 offset:33792
	ds_read_b128 v[142:145], v218 offset:34816
	ds_read_b128 v[154:157], v218 offset:35840
	ds_read_b128 v[162:165], v218 offset:36864
	ds_read_b128 v[170:173], v218 offset:37888
	ds_read_b128 v[174:177], v218 offset:38912
	ds_read_b128 v[186:189], v218 offset:39936
	global_load_lds_dwordx4 v[146:147], off
	v_lshl_add_u64 v[146:147], s[14:15], 0, v[180:181]
	s_mov_b32 m0, s26
	s_nop 0
	global_load_lds_dwordx4 v[146:147], off
	s_waitcnt lgkmcnt(8)
	s_waitcnt vmcnt(10)
	s_barrier
	s_waitcnt lgkmcnt(0)
	s_waitcnt lgkmcnt(0)
	v_mfma_f32_16x16x32_bf16 v[146:149], v[114:117], v[134:137], v[166:169]
	v_mfma_f32_16x16x32_bf16 v[166:169], v[118:121], v[138:141], v[146:149]
	v_mfma_f32_16x16x32_bf16 v[146:149], v[122:125], v[134:137], v[158:161]
	v_mfma_f32_16x16x32_bf16 v[110:113], v[114:117], v[142:145], v[110:113]
	v_mfma_f32_16x16x32_bf16 v[106:109], v[122:125], v[142:145], v[106:109]
	v_mfma_f32_16x16x32_bf16 v[94:97], v[114:117], v[162:165], v[94:97]
	v_mfma_f32_16x16x32_bf16 v[90:93], v[122:125], v[162:165], v[90:93]
	v_mfma_f32_16x16x32_bf16 v[78:81], v[114:117], v[174:177], v[78:81]
	v_mfma_f32_16x16x32_bf16 v[74:77], v[122:125], v[174:177], v[74:77]
	v_mfma_f32_16x16x32_bf16 v[158:161], v[126:129], v[138:141], v[146:149]
	v_mfma_f32_16x16x32_bf16 v[110:113], v[118:121], v[154:157], v[110:113]
	v_mfma_f32_16x16x32_bf16 v[106:109], v[126:129], v[154:157], v[106:109]
	v_mfma_f32_16x16x32_bf16 v[94:97], v[118:121], v[170:173], v[94:97]
	v_mfma_f32_16x16x32_bf16 v[90:93], v[126:129], v[170:173], v[90:93]
	v_mfma_f32_16x16x32_bf16 v[78:81], v[118:121], v[186:189], v[78:81]
	v_mfma_f32_16x16x32_bf16 v[74:77], v[126:129], v[186:189], v[74:77]
	s_barrier
	s_add_i32 s14, 0, 0x1c000
	v_add_u32_e32 v146, s14, v216
	s_add_i32 s15, s16, s22
	ds_read_b128 v[190:193], v146
	ds_read_b128 v[194:197], v146 offset:1024
	ds_read_b128 v[206:209], v146 offset:2048
	ds_read_b128 v[210:213], v146 offset:3072
	v_lshl_add_u64 v[146:147], v[200:201], 0, s[78:79]
	s_mov_b32 m0, s15
	s_nop 0
	global_load_lds_dwordx4 v[146:147], off
	v_lshl_add_u64 v[146:147], v[220:221], 0, s[78:79]
	s_add_i32 m0, s15, 0x2000
	s_nop 0
	global_load_lds_dwordx4 v[146:147], off
	s_waitcnt vmcnt(10)
	s_barrier
	s_waitcnt lgkmcnt(0)
	s_waitcnt lgkmcnt(0)
	v_mfma_f32_16x16x32_bf16 v[146:149], v[190:193], v[134:137], v[150:153]
	v_mfma_f32_16x16x32_bf16 v[130:133], v[206:209], v[134:137], v[130:133]
	v_mfma_f32_16x16x32_bf16 v[102:105], v[190:193], v[142:145], v[102:105]
	v_mfma_f32_16x16x32_bf16 v[98:101], v[206:209], v[142:145], v[98:101]
	v_mfma_f32_16x16x32_bf16 v[86:89], v[190:193], v[162:165], v[86:89]
	v_mfma_f32_16x16x32_bf16 v[82:85], v[206:209], v[162:165], v[82:85]
	v_mfma_f32_16x16x32_bf16 v[70:73], v[190:193], v[174:177], v[70:73]
	v_mfma_f32_16x16x32_bf16 v[66:69], v[206:209], v[174:177], v[66:69]
	v_mfma_f32_16x16x32_bf16 v[150:153], v[194:197], v[138:141], v[146:149]
	v_mfma_f32_16x16x32_bf16 v[146:149], v[210:213], v[138:141], v[130:133]
	v_mfma_f32_16x16x32_bf16 v[102:105], v[194:197], v[154:157], v[102:105]
	v_mfma_f32_16x16x32_bf16 v[98:101], v[210:213], v[154:157], v[98:101]
	v_mfma_f32_16x16x32_bf16 v[86:89], v[194:197], v[170:173], v[86:89]
	v_mfma_f32_16x16x32_bf16 v[82:85], v[210:213], v[170:173], v[82:85]
	v_mfma_f32_16x16x32_bf16 v[70:73], v[194:197], v[186:189], v[70:73]
	v_mfma_f32_16x16x32_bf16 v[66:69], v[210:213], v[186:189], v[66:69]
	s_mov_b32 m0, s28
	v_lshl_add_u64 v[186:187], v[222:223], 0, s[78:79]
	s_barrier
	ds_read_b128 v[130:133], v218 offset:49152
	ds_read_b128 v[134:137], v218 offset:50176
	ds_read_b128 v[138:141], v218 offset:51200
	ds_read_b128 v[142:145], v218 offset:52224
	ds_read_b128 v[154:157], v218 offset:53248
	ds_read_b128 v[162:165], v218 offset:54272
	ds_read_b128 v[170:173], v218 offset:55296
	ds_read_b128 v[174:177], v218 offset:56320
	global_load_lds_dwordx4 v[186:187], off
	v_lshl_add_u64 v[186:187], v[224:225], 0, s[78:79]
	s_mov_b32 m0, s29
	s_nop 0
	global_load_lds_dwordx4 v[186:187], off
	s_barrier
	s_waitcnt lgkmcnt(0)
	s_waitcnt lgkmcnt(0)
	v_mfma_f32_16x16x32_bf16 v[62:65], v[114:117], v[130:133], v[62:65]
	v_mfma_f32_16x16x32_bf16 v[58:61], v[122:125], v[130:133], v[58:61]
	v_mfma_f32_16x16x32_bf16 v[46:49], v[114:117], v[138:141], v[46:49]
	v_mfma_f32_16x16x32_bf16 v[42:45], v[122:125], v[138:141], v[42:45]
	v_mfma_f32_16x16x32_bf16 v[30:33], v[114:117], v[154:157], v[30:33]
	v_mfma_f32_16x16x32_bf16 v[26:29], v[122:125], v[154:157], v[26:29]
	v_mfma_f32_16x16x32_bf16 v[14:17], v[114:117], v[170:173], v[14:17]
	v_mfma_f32_16x16x32_bf16 v[10:13], v[122:125], v[170:173], v[10:13]
	v_mfma_f32_16x16x32_bf16 v[62:65], v[118:121], v[134:137], v[62:65]
	v_mfma_f32_16x16x32_bf16 v[58:61], v[126:129], v[134:137], v[58:61]
	v_mfma_f32_16x16x32_bf16 v[46:49], v[118:121], v[142:145], v[46:49]
	v_mfma_f32_16x16x32_bf16 v[42:45], v[126:129], v[142:145], v[42:45]
	v_mfma_f32_16x16x32_bf16 v[30:33], v[118:121], v[162:165], v[30:33]
	v_mfma_f32_16x16x32_bf16 v[26:29], v[126:129], v[162:165], v[26:29]
	v_mfma_f32_16x16x32_bf16 v[14:17], v[118:121], v[174:177], v[14:17]
	v_mfma_f32_16x16x32_bf16 v[10:13], v[126:129], v[174:177], v[10:13]
	s_barrier
	s_add_i32 s14, s14, s22
	v_lshl_add_u64 v[114:115], v[226:227], 0, s[78:79]
	s_mov_b32 m0, s14
	s_nop 0
	global_load_lds_dwordx4 v[114:115], off
	v_lshl_add_u64 v[114:115], v[228:229], 0, s[78:79]
	s_add_i32 m0, s14, 0x2000
	s_nop 0
	global_load_lds_dwordx4 v[114:115], off
	s_waitcnt vmcnt(10)
	s_barrier
	v_mfma_f32_16x16x32_bf16 v[54:57], v[190:193], v[130:133], v[54:57]
	v_mfma_f32_16x16x32_bf16 v[50:53], v[206:209], v[130:133], v[50:53]
	v_mfma_f32_16x16x32_bf16 v[38:41], v[190:193], v[138:141], v[38:41]
	v_mfma_f32_16x16x32_bf16 v[34:37], v[206:209], v[138:141], v[34:37]
	v_mfma_f32_16x16x32_bf16 v[22:25], v[190:193], v[154:157], v[22:25]
	v_mfma_f32_16x16x32_bf16 v[18:21], v[206:209], v[154:157], v[18:21]
	v_mfma_f32_16x16x32_bf16 v[6:9], v[190:193], v[170:173], v[6:9]
	v_mfma_f32_16x16x32_bf16 v[2:5], v[206:209], v[170:173], v[2:5]
	v_mfma_f32_16x16x32_bf16 v[54:57], v[194:197], v[134:137], v[54:57]
	v_mfma_f32_16x16x32_bf16 v[50:53], v[210:213], v[134:137], v[50:53]
	v_mfma_f32_16x16x32_bf16 v[38:41], v[194:197], v[142:145], v[38:41]
	v_mfma_f32_16x16x32_bf16 v[34:37], v[210:213], v[142:145], v[34:37]
	v_mfma_f32_16x16x32_bf16 v[22:25], v[194:197], v[162:165], v[22:25]
	v_mfma_f32_16x16x32_bf16 v[18:21], v[210:213], v[162:165], v[18:21]
	v_mfma_f32_16x16x32_bf16 v[6:9], v[194:197], v[174:177], v[6:9]
	v_mfma_f32_16x16x32_bf16 v[2:5], v[210:213], v[174:177], v[2:5]
	s_add_u32 s12, s12, 0x100
	s_addc_u32 s13, s13, 0
	s_add_u32 s38, s38, 0x100
	s_addc_u32 s39, s39, 0
	s_cmp_ge_u32 s40, s27
	s_mov_b32 s14, s40
	s_barrier
	s_cbranch_scc0 .LBB0_1348
	v_readlane_b32 s100, v254, 20
	s_nop 1
	s_cmp_lg_u32 s100, 3
	s_cselect_b64 s[100:101], -1, 0
	s_and_b64 s[0:1], s[0:1], s[100:101]
	v_lshl_add_u32 v190, s37, 8, v179
	v_lshl_or_b32 v186, s36, 8, v217
	v_ashrrev_i32_e32 v187, 31, v186
	v_ashrrev_i32_e32 v191, 31, v190
	v_lshl_add_u64 v[188:189], v[186:187], 2, s[10:11]
	v_lshlrev_b64 v[114:115], 13, v[190:191]
	v_lshl_add_u64 v[114:115], v[188:189], 0, v[114:115]
	global_load_dwordx4 v[206:209], v[114:115], off
	global_load_dwordx4 v[210:213], v[114:115], off offset:64
	global_load_dwordx4 v[220:223], v[114:115], off offset:512
	global_load_dwordx4 v[224:227], v[114:115], off offset:576
	v_or_b32_e32 v196, 16, v190
	v_ashrrev_i32_e32 v197, 31, v196
	v_lshlrev_b64 v[114:115], 13, v[196:197]
	v_or_b32_e32 v194, 32, v190
	v_lshl_add_u64 v[114:115], v[188:189], 0, v[114:115]
	v_ashrrev_i32_e32 v195, 31, v194
	global_load_dwordx4 v[174:177], v[114:115], off
	global_load_dwordx4 v[170:173], v[114:115], off offset:64
	global_load_dwordx4 v[162:165], v[114:115], off offset:512
	global_load_dwordx4 v[154:157], v[114:115], off offset:576
	v_lshlrev_b64 v[114:115], 13, v[194:195]
	v_or_b32_e32 v192, 48, v190
	v_lshl_add_u64 v[114:115], v[188:189], 0, v[114:115]
	v_ashrrev_i32_e32 v193, 31, v192
	global_load_dwordx4 v[142:145], v[114:115], off
	global_load_dwordx4 v[138:141], v[114:115], off offset:64
	global_load_dwordx4 v[130:133], v[114:115], off offset:512
	global_load_dwordx4 v[122:125], v[114:115], off offset:576
	v_lshlrev_b64 v[114:115], 13, v[192:193]
	v_lshl_add_u64 v[114:115], v[188:189], 0, v[114:115]
	global_load_dwordx4 v[134:137], v[114:115], off
	global_load_dwordx4 v[126:129], v[114:115], off offset:64
	global_load_dwordx4 v[118:121], v[114:115], off offset:512
	s_nop 0
	global_load_dwordx4 v[114:117], v[114:115], off offset:576
	v_lshlrev_b64 v[200:201], 11, v[190:191]
	v_lshl_add_u64 v[200:201], v[200:201], 0, v[186:187]
	v_readlane_b32 s12, v252, 35
	v_readlane_b32 s13, v252, 36
	s_waitcnt vmcnt(0)
	v_pk_add_f32 v[166:167], v[166:167], v[206:207]
	s_nop 0
	v_mul_f32_e32 v199, v167, v167
	v_pk_add_f32 v[168:169], v[168:169], v[208:209]
	v_fmac_f32_e32 v199, v166, v166
	v_lshl_add_u64 v[206:207], v[200:201], 2, s[72:73]
	v_fmac_f32_e32 v199, v168, v168
	global_store_dwordx4 v[206:207], v[166:169], off
	v_fmac_f32_e32 v199, v169, v169
	v_pk_add_f32 v[158:159], v[158:159], v[210:211]
	v_cvt_pk_bf16_f32 v166, v166, v167
	v_cvt_pk_bf16_f32 v167, v168, v169
	v_lshlrev_b64 v[168:169], 1, v[200:201]
	v_lshl_add_u64 v[200:201], s[12:13], 0, v[168:169]
	s_mov_b64 exec, s[100:101]
	global_store_dwordx2 v[200:201], v[166:167], off
	s_mov_b64 exec, -1
	v_mul_f32_e32 v166, v159, v159
	v_pk_add_f32 v[160:161], v[160:161], v[212:213]
	v_fmac_f32_e32 v166, v158, v158
	v_fmac_f32_e32 v166, v160, v160
	global_store_dwordx4 v[206:207], v[158:161], off offset:64
	v_fmac_f32_e32 v166, v161, v161
	v_pk_add_f32 v[150:151], v[150:151], v[220:221]
	v_cvt_pk_bf16_f32 v158, v158, v159
	v_cvt_pk_bf16_f32 v159, v160, v161
	v_or_b32_e32 v160, 32, v168
	v_mov_b32_e32 v161, v169
	v_lshl_add_u64 v[160:161], s[12:13], 0, v[160:161]
	s_mov_b64 exec, s[100:101]
	global_store_dwordx2 v[160:161], v[158:159], off
	s_mov_b64 exec, -1
	v_mul_f32_e32 v158, v151, v151
	v_pk_add_f32 v[152:153], v[152:153], v[222:223]
	v_fmac_f32_e32 v158, v150, v150
	v_fmac_f32_e32 v158, v152, v152
	global_store_dwordx4 v[206:207], v[150:153], off offset:512
	v_fmac_f32_e32 v158, v153, v153
	v_pk_add_f32 v[146:147], v[146:147], v[224:225]
	v_cvt_pk_bf16_f32 v150, v150, v151
	v_cvt_pk_bf16_f32 v151, v152, v153
	v_or_b32_e32 v152, 0x100, v168
	v_mov_b32_e32 v153, v169
	v_lshl_add_u64 v[152:153], s[12:13], 0, v[152:153]
	s_mov_b64 exec, s[100:101]
	global_store_dwordx2 v[152:153], v[150:151], off
	s_mov_b64 exec, -1
	v_mul_f32_e32 v150, v147, v147
	v_pk_add_f32 v[148:149], v[148:149], v[226:227]
	v_fmac_f32_e32 v150, v146, v146
	v_fmac_f32_e32 v150, v148, v148
	v_or_b32_e32 v168, 0x120, v168
	global_store_dwordx4 v[206:207], v[146:149], off offset:576
	v_fmac_f32_e32 v150, v149, v149
	v_add_f32_e32 v166, v199, v166
	v_cvt_pk_bf16_f32 v146, v146, v147
	v_cvt_pk_bf16_f32 v147, v148, v149
	v_lshl_add_u64 v[148:149], s[12:13], 0, v[168:169]
	s_mov_b64 exec, s[100:101]
	global_store_dwordx2 v[148:149], v[146:147], off
	s_mov_b64 exec, -1
	v_and_b32_e32 v147, 64, v205
	v_xor_b32_e32 v146, 16, v205
	v_add_u32_e32 v147, 64, v147
	v_cmp_lt_i32_e32 vcc, v146, v147
	v_add_f32_e32 v158, v166, v158
	v_add_f32_e32 v150, v158, v150
	v_cndmask_b32_e32 v146, v205, v146, vcc
	v_lshlrev_b32_e32 v166, 2, v146
	ds_bpermute_b32 v146, v166, v150
	v_xor_b32_e32 v148, 32, v205
	v_cmp_lt_i32_e32 vcc, v148, v147
	s_waitcnt lgkmcnt(0)
	v_add_f32_e32 v146, v150, v146
	v_cndmask_b32_e32 v147, v205, v148, vcc
	v_lshlrev_b32_e32 v167, 2, v147
	ds_bpermute_b32 v147, v167, v146
	s_and_saveexec_b64 s[12:13], s[0:1]
	s_cbranch_execz .LBB0_1351
	v_readlane_b32 s14, v252, 28
	v_readlane_b32 s15, v252, 29
	s_waitcnt lgkmcnt(0)
	v_add_f32_e32 v146, v146, v147
	v_lshl_add_u64 v[148:149], v[190:191], 2, s[14:15]
	global_atomic_add_f32 v[148:149], v146, off
